# non-temporal hint on the decode-group RWKV state / record copies and the retention output chunks' last-use operand loads
# speedup vs baseline: 1.0353x; 1.0353x over previous
.LBB0_394:
	v_ashrrev_i32_e32 v1, 31, v0
	v_lshl_add_u64 v[4:5], s[18:19], 0, v[0:1]
	global_load_dwordx4 v[4:7], v[4:5], off nt
	v_add_u32_e32 v2, 0x200, v2
	s_movk_i32 s8, 0x27f
	v_cmp_lt_i32_e32 vcc, s8, v2
	v_add_u32_e32 v1, 0, v0
	s_or_b64 s[20:21], vcc, s[20:21]
	v_add_u32_e32 v0, 0x2000, v0
	s_waitcnt vmcnt(0)
	ds_write_b128 v1, v[4:7]
	s_andn2_b64 exec, exec, s[20:21]
	s_cbranch_execnz .LBB0_394
.LBB0_395:
	s_or_b64 exec, exec, s[16:17]
	s_ashr_i32 s18, s0, 3
	s_ashr_i32 s16, s3, 6
	v_bfe_u32 v126, v124, 5, 1
	s_cmp_gt_i32 s16, 1
	v_and_b32_e32 v125, 31, v124
	s_cselect_b64 s[20:21], -1, 0
	s_cmp_lt_i32 s16, 2
	v_mov_b32_e32 v0, 0
	v_lshlrev_b32_e32 v156, 4, v126
	v_mov_b32_e32 v1, 0
	v_mov_b32_e32 v2, 0
	v_mov_b32_e32 v3, 0
	v_mov_b32_e32 v4, 0
	v_mov_b32_e32 v5, 0
	v_mov_b32_e32 v6, 0
	v_mov_b32_e32 v7, 0
	v_mov_b32_e32 v8, 0
	v_mov_b32_e32 v9, 0
	v_mov_b32_e32 v10, 0
	v_mov_b32_e32 v11, 0
	v_mov_b32_e32 v12, 0
	v_mov_b32_e32 v13, 0
	v_mov_b32_e32 v14, 0
	v_mov_b32_e32 v15, 0
	v_mov_b32_e32 v16, 0
	v_mov_b32_e32 v17, 0
	v_mov_b32_e32 v18, 0
	v_mov_b32_e32 v19, 0
	v_mov_b32_e32 v20, 0
	v_mov_b32_e32 v21, 0
	v_mov_b32_e32 v22, 0
	v_mov_b32_e32 v23, 0
	v_mov_b32_e32 v24, 0
	v_mov_b32_e32 v25, 0
	v_mov_b32_e32 v26, 0
	v_mov_b32_e32 v27, 0
	v_mov_b32_e32 v28, 0
	v_mov_b32_e32 v29, 0
	v_mov_b32_e32 v30, 0
	v_mov_b32_e32 v31, 0
	s_cbranch_scc0 .LBB0_397
	s_ashr_i32 s19, s18, 31
	s_load_dwordx2 s[8:9], s[14:15], 0x28
	s_lshl_b64 s[22:23], s[18:19], 9
	s_lshl_b32 s13, s5, 6
	s_or_b32 s13, s22, s13
	s_lshl_b32 s24, s16, 5
	s_ashr_i32 s25, s24, 31
	v_or_b32_e32 v0, s13, v125
	v_mov_b32_e32 v1, s23
	v_lshl_add_u64 v[0:1], v[0:1], 0, s[24:25]
	v_lshlrev_b64 v[0:1], 8, v[0:1]
	s_waitcnt lgkmcnt(0)
	v_lshl_add_u64 v[0:1], s[8:9], 0, v[0:1]
	v_lshl_add_u64 v[28:29], v[0:1], 0, v[156:157]
	global_load_dwordx4 v[0:3], v[28:29], off nt
	global_load_dwordx4 v[4:7], v[28:29], off offset:32 nt
	global_load_dwordx4 v[8:11], v[28:29], off offset:64 nt
	global_load_dwordx4 v[12:15], v[28:29], off offset:96 nt
	global_load_dwordx4 v[16:19], v[28:29], off offset:128 nt
	global_load_dwordx4 v[20:23], v[28:29], off offset:160 nt
	global_load_dwordx4 v[24:27], v[28:29], off offset:192 nt
	s_nop 0
	global_load_dwordx4 v[28:31], v[28:29], off offset:224 nt

.LBB0_399:
	s_andn2_b64 vcc, exec, s[20:21]
	s_cbranch_vccnz .LBB0_391
	s_lshl_b32 s20, s16, 5
	v_or_b32_e32 v32, s20, v125
	v_and_b32_e32 v36, 15, v124
	v_mul_lo_u32 v32, v32, 48
	v_mad_u32_u24 v37, v36, s42, 0
	v_lshlrev_b32_e32 v38, 3, v126
	v_mul_i32_i24_e32 v36, 0xffffffa8, v36
	v_add3_u32 v32, 0, v32, v156
	v_add_u32_e32 v39, v37, v38
	v_add3_u32 v36, v37, v36, v156
	ds_read_b128 v[48:51], v32 offset:14720
	ds_read2_b64 v[32:35], v39 offset1:2
	ds_read2_b64 v[52:55], v39 offset0:4 offset1:6
	ds_read2_b64 v[56:59], v39 offset0:8 offset1:10
	ds_read2_b64 v[60:63], v39 offset0:12 offset1:14
	ds_read_b128 v[64:67], v36 offset:2176
	v_add_u32_e32 v36, 0, v38
	v_add_u32_e32 v127, v36, v38
	v_mad_u32_u24 v36, v125, s42, v36
	v_add_u32_e32 v37, 0x800, v36
	ds_read2_b64 v[84:87], v37 offset0:112 offset1:114
	ds_read2_b64 v[68:71], v37 offset0:116 offset1:118
	ds_read2_b64 v[72:75], v37 offset0:120 offset1:122
	ds_read2_b64 v[76:79], v37 offset0:124 offset1:126
	v_mad_u32_u24 v37, v125, 48, v127
	v_add_u32_e32 v36, 0x1800, v36
	ds_read_b128 v[80:83], v37 offset:11648
	ds_read2_b64 v[88:91], v36 offset0:144 offset1:146
	ds_read2_b64 v[92:95], v36 offset0:148 offset1:150
	ds_read2_b64 v[96:99], v36 offset0:152 offset1:154
	ds_read2_b64 v[100:103], v36 offset0:156 offset1:158
	ds_read_b128 v[104:107], v37 offset:13184
	s_waitcnt vmcnt(0)
	v_cvt_pk_bf16_f32 v108, v0, v1
	v_cvt_pk_bf16_f32 v109, v2, v3
	v_cvt_pk_bf16_f32 v110, v4, v5
	v_cvt_pk_bf16_f32 v111, v6, v7
	v_cvt_pk_bf16_f32 v112, v8, v9
	v_cvt_pk_bf16_f32 v113, v10, v11
	v_cvt_pk_bf16_f32 v114, v12, v13
	v_cvt_pk_bf16_f32 v115, v14, v15
	v_cvt_pk_bf16_f32 v116, v16, v17
	v_cvt_pk_bf16_f32 v117, v18, v19
	v_cvt_pk_bf16_f32 v118, v20, v21
	v_cvt_pk_bf16_f32 v119, v22, v23
	v_cvt_pk_bf16_f32 v120, v24, v25
	v_cvt_pk_bf16_f32 v121, v26, v27
	v_cvt_pk_bf16_f32 v122, v28, v29
	v_cvt_pk_bf16_f32 v123, v30, v31
	ds_read_b128 v[36:39], v127 offset:17792
	ds_read_b128 v[40:43], v127 offset:17824
	s_movk_i32 s8, 0x3f0
	s_ashr_i32 s19, s18, 31
	s_lshl_b64 s[18:19], s[18:19], 9
	s_waitcnt lgkmcnt(1)
	v_pk_mul_f32 v[0:1], v[0:1], v[36:37]
	v_pk_mul_f32 v[2:3], v[2:3], v[38:39]
	ds_read_b128 v[36:39], v127 offset:17856
	s_waitcnt lgkmcnt(1)
	v_pk_mul_f32 v[4:5], v[4:5], v[40:41]
	v_pk_mul_f32 v[6:7], v[6:7], v[42:43]
	s_ashr_i32 s21, s20, 31
	s_waitcnt lgkmcnt(0)
	v_pk_mul_f32 v[8:9], v[8:9], v[36:37]
	v_pk_mul_f32 v[10:11], v[10:11], v[38:39]
	ds_read_b128 v[36:39], v127 offset:17888
	s_waitcnt lgkmcnt(0)
	v_pk_mul_f32 v[12:13], v[12:13], v[36:37]
	v_pk_mul_f32 v[14:15], v[14:15], v[38:39]
	ds_read_b128 v[36:39], v127 offset:17920
	s_waitcnt lgkmcnt(0)
	v_pk_mul_f32 v[16:17], v[16:17], v[36:37]
	v_pk_mul_f32 v[18:19], v[18:19], v[38:39]
	ds_read_b128 v[36:39], v127 offset:17952
	v_mfma_f32_32x32x16_bf16 v[0:15], v[84:87], v[108:111], v[0:15]
	s_waitcnt lgkmcnt(0)
	v_mul_f32_e64 v20, v20, v36
	v_mul_f32_e64 v21, v21, v37
	v_mul_f32_e64 v22, v22, v38
	v_mul_f32_e64 v23, v23, v39
	ds_read_b128 v[36:39], v127 offset:17984
	s_waitcnt lgkmcnt(0)
	v_pk_mul_f32 v[24:25], v[24:25], v[36:37]
	v_pk_mul_f32 v[26:27], v[26:27], v[38:39]
	ds_read_b128 v[36:39], v127 offset:18016
	v_mfma_f32_32x32x16_bf16 v[0:15], v[68:71], v[112:115], v[0:15]
	s_waitcnt lgkmcnt(0)
	v_mul_f32_e64 v28, v28, v36
	v_mul_f32_e64 v29, v29, v37
	v_mul_f32_e64 v30, v30, v38
	v_mul_f32_e64 v31, v31, v39
	v_mfma_f32_32x32x16_bf16 v[32:47], v[32:35], v[108:111], 0
	v_mfma_f32_32x32x16_bf16 v[32:47], v[52:55], v[112:115], v[32:47]
	v_mfma_f32_32x32x16_bf16 v[16:31], v[88:91], v[108:111], v[16:31]
	v_mfma_f32_32x32x16_bf16 v[32:47], v[56:59], v[116:119], v[32:47]
	v_mfma_f32_32x32x16_bf16 v[16:31], v[92:95], v[112:115], v[16:31]
	v_mfma_f32_32x32x16_bf16 v[32:47], v[60:63], v[120:123], v[32:47]
	v_mfma_f32_32x32x16_bf16 v[0:15], v[72:75], v[116:119], v[0:15]
	v_mfma_f32_32x32x16_bf16 v[16:31], v[96:99], v[116:119], v[16:31]
	v_mfma_f32_32x32x16_bf16 v[32:47], v[64:67], v[48:51], v[32:47]
	v_mfma_f32_32x32x16_bf16 v[0:15], v[76:79], v[120:123], v[0:15]
	s_nop 10
	v_mad_u32_u24 v40, v126, s8, v127
	s_lshl_b32 s8, s16, 7
	v_lshlrev_b32_e32 v41, 2, v125
	v_add3_u32 v40, v40, s8, v41
	ds_write2st64_b32 v40, v32, v33 offset0:72 offset1:73
	ds_write2st64_b32 v40, v34, v35 offset0:74 offset1:75
	ds_write2st64_b32 v40, v36, v37 offset0:80 offset1:81
	ds_write2st64_b32 v40, v38, v39 offset0:82 offset1:83
	s_load_dwordx2 s[22:23], s[14:15], 0x150
	s_lshl_b32 s8, s5, 6
	v_mfma_f32_32x32x16_bf16 v[16:31], v[100:103], v[120:123], v[16:31]
	s_or_b32 s5, s18, s8
	v_or_b32_e32 v32, s5, v125
	v_mov_b32_e32 v33, s19
	v_lshl_add_u64 v[32:33], v[32:33], 0, s[20:21]
	v_lshlrev_b64 v[32:33], 8, v[32:33]
	s_waitcnt lgkmcnt(0)
	v_lshl_add_u64 v[32:33], s[22:23], 0, v[32:33]
	v_lshl_add_u64 v[32:33], v[32:33], 0, v[156:157]
	v_mfma_f32_32x32x16_bf16 v[0:15], v[80:83], v[48:51], v[0:15]
	s_mov_b64 s[18:19], 0xa996000
	s_mov_b32 s5, 0xa996000
	v_lshl_add_u64 v[34:35], v[32:33], 0, s[18:19]
	v_add_co_u32_e32 v32, vcc, s5, v32
	s_nop 1
	v_addc_co_u32_e32 v33, vcc, 0, v33, vcc
	v_mfma_f32_32x32x16_bf16 v[16:31], v[104:107], v[48:51], v[16:31]
	s_nop 3
	global_store_dwordx4 v[32:33], v[0:3], off nt
	global_store_dwordx4 v[34:35], v[4:7], off offset:32 nt
	global_store_dwordx4 v[34:35], v[8:11], off offset:64 nt
	global_store_dwordx4 v[34:35], v[12:15], off offset:96 nt
	s_nop 3
	global_store_dwordx4 v[34:35], v[16:19], off offset:128 nt
	global_store_dwordx4 v[34:35], v[20:23], off offset:160 nt
	global_store_dwordx4 v[34:35], v[24:27], off offset:192 nt
	global_store_dwordx4 v[34:35], v[28:31], off offset:224 nt
	s_branch .LBB0_391

.LBB0_403:
	s_mov_b64 s[0:1], s[58:59]
	s_load_dwordx2 s[0:1], s[0:1], 0x158
	s_mov_b64 s[12:13], s[58:59]
	s_mov_b64 s[14:15], s[58:59]
	s_load_dwordx2 s[18:19], s[12:13], 0x158
	s_waitcnt lgkmcnt(0)
	s_add_u32 s20, s0, 0x12f00000
	s_addc_u32 s21, s1, 0
	s_mov_b64 s[0:1], s[58:59]
	s_load_dwordx2 s[12:13], s[14:15], 0xa8
	s_load_dwordx2 s[14:15], s[0:1], 0x158
	v_mbcnt_lo_u32_b32 v18, -1, 0
	v_mbcnt_hi_u32_b32 v18, -1, v18
	s_and_b32 s0, s8, 0xfffff800
	v_add_u32_e32 v20, s61, v18
	s_and_b32 s5, s24, 0x7c0
	s_or_b32 s16, s0, s5
	v_ashrrev_i32_e32 v19, 3, v20
	s_bfe_u32 s3, s2, 0x20005
	v_lshlrev_b32_e32 v9, 3, v20
	v_add_u32_e32 v3, s16, v19
	v_mov_b64_e32 v[0:1], s[20:21]
	v_and_b32_e32 v2, 56, v9
	v_mad_i64_i32 v[0:1], s[0:1], v3, s83, v[0:1]
	s_lshl_b32 s30, s3, 8
	v_lshl_add_u64 v[0:1], v[0:1], 0, s[30:31]
	v_lshlrev_b32_e32 v156, 1, v2
	v_lshl_add_u64 v[0:1], v[0:1], 0, v[156:157]
	global_load_dwordx4 v[22:25], v[0:1], off offset:2048 nt
	global_load_dwordx4 v[26:29], v[0:1], off offset:2176 nt
	v_subrev_u32_e32 v3, 32, v19
	v_sub_u32_e32 v4, 32, v19
	v_bitop3_b32 v5, v19, 56, v9 bitop3:0x48
	v_lshlrev_b32_e32 v6, 1, v19
	v_cvt_f32_ubyte0_e32 v7, s3
	v_lshl_add_u32 v8, v2, 2, 0
	v_cvt_f32_i32_e32 v48, v3
	v_cvt_f32_i32_e32 v49, v4
	v_add_u32_e32 v3, s5, v19
	v_lshl_add_u32 v4, v5, 1, 0
	v_and_b32_e32 v5, 14, v6
	v_mul_u32_u24_e32 v2, 0x90, v2
	v_sub_f32_e32 v6, 0xc0a00000, v7
	v_add_u32_e32 v7, 0x22400, v8
	v_cvt_f32_i32_e32 v50, v3
	v_add3_u32 v51, v4, v5, v2
	v_add3_u32 v52, v4, v2, v5
	v_exp_f32_e32 v8, v6
	ds_read_b128 v[12:15], v7
	ds_read_b128 v[30:33], v7 offset:16
	global_load_dwordx4 v[34:37], v[0:1], off nt
	global_load_dwordx4 v[38:41], v[0:1], off offset:128 nt
	global_load_dwordx4 v[4:7], v[0:1], off offset:1024 nt
	s_nop 0
	global_load_dwordx4 v[0:3], v[0:1], off offset:1152 nt
	s_lshl_b32 s3, s3, 7
	v_sub_f32_e32 v8, 1.0, v8
	v_log_f32_e32 v21, v8
	s_waitcnt lgkmcnt(0)
	v_mul_f32_e32 v8, v12, v50
	v_mul_f32_e32 v12, v13, v50
	v_mul_f32_e32 v14, v14, v50
	v_cvt_f64_f32_e32 v[10:11], v8
	v_cvt_f64_f32_e32 v[12:13], v12
	v_cvt_f64_f32_e32 v[16:17], v14
	v_mul_f64 v[42:43], v[10:11], s[86:87]
	v_mul_f64 v[44:45], v[12:13], s[86:87]
	v_mul_f64 v[46:47], v[16:17], s[86:87]
	v_rndne_f64_e32 v[42:43], v[42:43]
	v_rndne_f64_e32 v[44:45], v[44:45]
	v_rndne_f64_e32 v[46:47], v[46:47]
	v_fma_f64 v[10:11], v[10:11], s[86:87], -v[42:43]
	v_fma_f64 v[12:13], v[12:13], s[86:87], -v[44:45]
	v_mul_f32_e32 v8, v21, v48
	v_mul_f32_e32 v14, v21, v49
	v_fma_f64 v[16:17], v[16:17], s[86:87], -v[46:47]
	v_cvt_f32_f64_e32 v10, v[10:11]
	v_cvt_f32_f64_e32 v11, v[12:13]
	v_exp_f32_e32 v42, v8
	v_exp_f32_e32 v8, v14
	v_cvt_f32_f64_e32 v17, v[16:17]
	v_sin_f32_e32 v12, v10
	v_cos_f32_e32 v16, v10
	v_sin_f32_e32 v10, v11
	v_cos_f32_e32 v14, v11
	v_mul_f32_e32 v11, v15, v50
	v_cvt_f64_f32_e32 v[44:45], v11
	v_mul_f64 v[46:47], v[44:45], s[86:87]
	v_rndne_f64_e32 v[46:47], v[46:47]
	v_fma_f64 v[44:45], v[44:45], s[86:87], -v[46:47]
	v_cvt_f32_f64_e32 v15, v[44:45]
	v_sin_f32_e32 v11, v15
	v_sin_f32_e32 v13, v17
	v_cos_f32_e32 v15, v15
	v_cos_f32_e32 v17, v17
	v_mul_f32_e32 v8, 0x3db504f3, v8
	v_cmp_gt_i32_e32 vcc, s77, v20
	s_waitcnt vmcnt(5)
	ds_write_b16 v51, v22 offset:44032
	s_waitcnt vmcnt(4)
	ds_write_b16 v52, v26 offset:53248
	ds_write_b16_d16_hi v51, v22 offset:44176
	ds_write_b16_d16_hi v52, v26 offset:53392
	ds_write_b16 v51, v23 offset:44320
	ds_write_b16 v52, v27 offset:53536
	v_mul_f32_e32 v22, v30, v50
	ds_write_b16_d16_hi v51, v23 offset:44464
	ds_write_b16_d16_hi v52, v27 offset:53680
	v_cvt_f64_f32_e32 v[22:23], v22
	v_mul_f64 v[26:27], v[22:23], s[86:87]
	v_rndne_f64_e32 v[26:27], v[26:27]
	v_fma_f64 v[22:23], v[22:23], s[86:87], -v[26:27]
	v_cvt_f32_f64_e32 v22, v[22:23]
	v_sin_f32_e32 v26, v22
	v_cos_f32_e32 v30, v22
	v_mul_f32_e32 v22, v31, v50
	v_cvt_f64_f32_e32 v[22:23], v22
	v_mul_f64 v[44:45], v[22:23], s[86:87]
	v_rndne_f64_e32 v[44:45], v[44:45]
	v_fma_f64 v[22:23], v[22:23], s[86:87], -v[44:45]
	v_cvt_f32_f64_e32 v22, v[22:23]
	v_sin_f32_e32 v44, v22
	v_cos_f32_e32 v46, v22
	v_mul_f32_e32 v22, v32, v50
	v_cvt_f64_f32_e32 v[22:23], v22
	v_mul_f64 v[48:49], v[22:23], s[86:87]
	v_rndne_f64_e32 v[48:49], v[48:49]
	v_fma_f64 v[22:23], v[22:23], s[86:87], -v[48:49]
	v_cvt_f32_f64_e32 v22, v[22:23]
	v_sin_f32_e32 v27, v22
	v_cos_f32_e32 v31, v22
	v_mul_f32_e32 v22, v33, v50
	v_cvt_f64_f32_e32 v[22:23], v22
	v_mul_f64 v[32:33], v[22:23], s[86:87]
	v_rndne_f64_e32 v[32:33], v[32:33]
	v_fma_f64 v[22:23], v[22:23], s[86:87], -v[32:33]
	v_cvt_f32_f64_e32 v22, v[22:23]
	v_sin_f32_e32 v45, v22
	v_cos_f32_e32 v47, v22
	ds_write_b16 v51, v24 offset:44608
	ds_write_b16 v52, v28 offset:53824
	ds_write_b16_d16_hi v51, v24 offset:44752
	ds_write_b16_d16_hi v52, v28 offset:53968
	ds_write_b16 v51, v25 offset:44896
	ds_write_b16 v52, v29 offset:54112
	ds_write_b16_d16_hi v51, v25 offset:45040
	ds_write_b16_d16_hi v52, v29 offset:54256
	s_waitcnt vmcnt(3)
	v_lshlrev_b32_e32 v29, 16, v35
	v_lshlrev_b32_e32 v28, 16, v34
	v_and_b32_e32 v33, 0xffff0000, v35
	v_and_b32_e32 v32, 0xffff0000, v34
	s_waitcnt vmcnt(2)
	v_lshlrev_b32_e32 v35, 16, v39
	v_lshlrev_b32_e32 v34, 16, v38
	v_and_b32_e32 v39, 0xffff0000, v39
	v_and_b32_e32 v38, 0xffff0000, v38
	v_lshlrev_b32_e32 v51, 16, v41
	v_lshlrev_b32_e32 v50, 16, v40
	v_and_b32_e32 v41, 0xffff0000, v41
	v_and_b32_e32 v40, 0xffff0000, v40
	v_pk_mul_f32 v[24:25], v[10:11], v[38:39]
	v_lshlrev_b32_e32 v49, 16, v37
	v_lshlrev_b32_e32 v48, 16, v36
	v_and_b32_e32 v37, 0xffff0000, v37
	v_and_b32_e32 v36, 0xffff0000, v36
	v_pk_mul_f32 v[54:55], v[44:45], v[40:41]
	v_pk_mul_f32 v[22:23], v[12:13], v[34:35]
	v_pk_fma_f32 v[24:25], v[14:15], v[32:33], v[24:25] neg_lo:[0,0,1] neg_hi:[0,0,1]
	v_pk_mul_f32 v[52:53], v[26:27], v[50:51]
	v_pk_fma_f32 v[54:55], v[46:47], v[36:37], v[54:55] neg_lo:[0,0,1] neg_hi:[0,0,1]
	v_pk_fma_f32 v[22:23], v[16:17], v[28:29], v[22:23] neg_lo:[0,0,1] neg_hi:[0,0,1]
	v_pk_mul_f32 v[24:25], v[42:43], v[24:25] op_sel_hi:[0,1]
	v_pk_fma_f32 v[52:53], v[30:31], v[48:49], v[52:53] neg_lo:[0,0,1] neg_hi:[0,0,1]
	v_pk_mul_f32 v[54:55], v[42:43], v[54:55] op_sel_hi:[0,1]
	v_pk_mul_f32 v[22:23], v[42:43], v[22:23] op_sel_hi:[0,1]
	v_pk_mul_f32 v[52:53], v[42:43], v[52:53] op_sel_hi:[0,1]
	v_bfe_u32 v43, v55, 16, 1
	v_bfe_u32 v57, v25, 16, 1
	v_bfe_u32 v56, v54, 16, 1
	v_bfe_u32 v58, v24, 16, 1
	v_add3_u32 v57, v25, v57, s54
	v_add3_u32 v25, v55, v43, s54
	v_bfe_u32 v55, v52, 16, 1
	v_add3_u32 v58, v24, v58, s54
	v_add3_u32 v24, v54, v56, s54
	v_bfe_u32 v43, v22, 16, 1
	v_bfe_u32 v54, v23, 16, 1
	v_bfe_u32 v56, v53, 16, 1
	v_add3_u32 v52, v52, v55, s54
	v_add3_u32 v53, v53, v56, s54
	v_add3_u32 v23, v23, v54, s54
	v_add3_u32 v22, v22, v43, s54
	v_lshrrev_b32_e32 v43, 16, v52
	v_lshrrev_b32_e32 v22, 16, v22
	v_lshrrev_b32_e32 v23, 16, v23
	v_lshrrev_b32_e32 v52, 16, v53
	v_and_or_b32 v24, v24, s33, v43
	v_mul_lo_u32 v43, v19, s29
	v_and_or_b32 v25, v25, s33, v52
	v_and_or_b32 v23, v57, s33, v23
	v_and_or_b32 v22, v58, s33, v22
	v_add3_u32 v43, 0, v43, v156
	ds_write_b128 v43, v[22:25]
	v_pk_mul_f32 v[24:25], v[14:15], v[38:39]
	v_pk_mul_f32 v[22:23], v[16:17], v[34:35]
	v_pk_fma_f32 v[24:25], v[10:11], v[32:33], v[24:25]
	v_pk_mul_f32 v[32:33], v[46:47], v[40:41]
	v_pk_fma_f32 v[22:23], v[12:13], v[28:29], v[22:23]
	v_pk_mul_f32 v[28:29], v[30:31], v[50:51]
	v_pk_fma_f32 v[32:33], v[44:45], v[36:37], v[32:33]
	v_pk_mul_f32 v[24:25], v[42:43], v[24:25] op_sel_hi:[0,1]
	v_pk_fma_f32 v[28:29], v[26:27], v[48:49], v[28:29]
	v_pk_mul_f32 v[32:33], v[42:43], v[32:33] op_sel_hi:[0,1]
	v_pk_mul_f32 v[22:23], v[42:43], v[22:23] op_sel_hi:[0,1]
	v_pk_mul_f32 v[28:29], v[42:43], v[28:29] op_sel_hi:[0,1]
	v_bfe_u32 v34, v33, 16, 1
	v_bfe_u32 v35, v32, 16, 1
	v_bfe_u32 v36, v25, 16, 1
	v_bfe_u32 v37, v24, 16, 1
	v_add3_u32 v37, v24, v37, s54
	v_add3_u32 v36, v25, v36, s54
	v_add3_u32 v24, v32, v35, s54
	v_add3_u32 v25, v33, v34, s54
	v_bfe_u32 v32, v22, 16, 1
	v_bfe_u32 v33, v23, 16, 1
	v_bfe_u32 v34, v28, 16, 1
	v_bfe_u32 v35, v29, 16, 1
	v_add3_u32 v29, v29, v35, s54
	v_add3_u32 v28, v28, v34, s54
	v_add3_u32 v23, v23, v33, s54
	v_add3_u32 v22, v22, v32, s54
	v_lshrrev_b32_e32 v22, 16, v22
	v_lshrrev_b32_e32 v23, 16, v23
	v_lshrrev_b32_e32 v28, 16, v28
	v_lshrrev_b32_e32 v29, 16, v29
	v_and_or_b32 v25, v25, s33, v29
	v_and_or_b32 v24, v24, s33, v28
	v_and_or_b32 v23, v36, s33, v23
	v_and_or_b32 v22, v37, s33, v22
	s_waitcnt vmcnt(0)
	v_and_b32_e32 v29, 0xffff0000, v1
	v_and_b32_e32 v28, 0xffff0000, v0
	v_and_b32_e32 v39, 0xffff0000, v3
	v_and_b32_e32 v38, 0xffff0000, v2
	ds_write_b128 v43, v[22:25] offset:128
	v_lshlrev_b32_e32 v23, 16, v5
	v_lshlrev_b32_e32 v22, 16, v4
	v_and_b32_e32 v5, 0xffff0000, v5
	v_and_b32_e32 v4, 0xffff0000, v4
	v_lshlrev_b32_e32 v25, 16, v1
	v_lshlrev_b32_e32 v24, 16, v0
	v_pk_mul_f32 v[32:33], v[10:11], v[28:29]
	v_lshlrev_b32_e32 v35, 16, v7
	v_lshlrev_b32_e32 v34, 16, v6
	v_and_b32_e32 v7, 0xffff0000, v7
	v_and_b32_e32 v6, 0xffff0000, v6
	v_lshlrev_b32_e32 v37, 16, v3
	v_lshlrev_b32_e32 v36, 16, v2
	v_pk_mul_f32 v[40:41], v[44:45], v[38:39]
	v_pk_mul_f32 v[0:1], v[12:13], v[24:25]
	v_pk_fma_f32 v[32:33], v[14:15], v[4:5], v[32:33] neg_lo:[0,0,1] neg_hi:[0,0,1]
	v_pk_mul_f32 v[2:3], v[26:27], v[36:37]
	v_pk_fma_f32 v[40:41], v[46:47], v[6:7], v[40:41] neg_lo:[0,0,1] neg_hi:[0,0,1]
	v_pk_fma_f32 v[0:1], v[16:17], v[22:23], v[0:1] neg_lo:[0,0,1] neg_hi:[0,0,1]
	v_pk_mul_f32 v[32:33], v[8:9], v[32:33] op_sel_hi:[0,1]
	v_pk_fma_f32 v[2:3], v[30:31], v[34:35], v[2:3] neg_lo:[0,0,1] neg_hi:[0,0,1]
	v_pk_mul_f32 v[40:41], v[8:9], v[40:41] op_sel_hi:[0,1]
	v_pk_mul_f32 v[0:1], v[8:9], v[0:1] op_sel_hi:[0,1]
	v_pk_mul_f32 v[2:3], v[8:9], v[2:3] op_sel_hi:[0,1]
	v_bfe_u32 v42, v41, 16, 1
	v_bfe_u32 v48, v40, 16, 1
	v_bfe_u32 v49, v33, 16, 1
	v_bfe_u32 v50, v32, 16, 1
	v_add3_u32 v32, v32, v50, s54
	v_add3_u32 v33, v33, v49, s54
	v_add3_u32 v40, v40, v48, s54
	v_add3_u32 v41, v41, v42, s54
	v_bfe_u32 v42, v0, 16, 1
	v_bfe_u32 v48, v1, 16, 1
	v_bfe_u32 v49, v2, 16, 1
	v_bfe_u32 v50, v3, 16, 1
	v_add3_u32 v3, v3, v50, s54
	v_add3_u32 v2, v2, v49, s54
	v_add3_u32 v1, v1, v48, s54
	v_add3_u32 v0, v0, v42, s54
	v_lshrrev_b32_e32 v0, 16, v0
	v_lshrrev_b32_e32 v1, 16, v1
	v_lshrrev_b32_e32 v2, 16, v2
	v_lshrrev_b32_e32 v3, 16, v3
	v_and_or_b32 v3, v41, s33, v3
	v_and_or_b32 v2, v40, s33, v2
	v_and_or_b32 v1, v33, s33, v1
	v_and_or_b32 v0, v32, s33, v0
	ds_write_b128 v43, v[0:3] offset:17408
	v_pk_mul_f32 v[2:3], v[14:15], v[28:29]
	v_pk_mul_f32 v[0:1], v[16:17], v[24:25]
	v_pk_fma_f32 v[2:3], v[10:11], v[4:5], v[2:3]
	v_pk_mul_f32 v[10:11], v[46:47], v[38:39]
	v_pk_mul_f32 v[4:5], v[30:31], v[36:37]
	v_pk_fma_f32 v[6:7], v[44:45], v[6:7], v[10:11]
	v_pk_fma_f32 v[0:1], v[12:13], v[22:23], v[0:1]
	v_pk_mul_f32 v[2:3], v[8:9], v[2:3] op_sel_hi:[0,1]
	v_pk_fma_f32 v[4:5], v[26:27], v[34:35], v[4:5]
	v_pk_mul_f32 v[6:7], v[8:9], v[6:7] op_sel_hi:[0,1]
	v_pk_mul_f32 v[0:1], v[8:9], v[0:1] op_sel_hi:[0,1]
	v_pk_mul_f32 v[4:5], v[8:9], v[4:5] op_sel_hi:[0,1]
	v_bfe_u32 v8, v7, 16, 1
	v_bfe_u32 v10, v6, 16, 1
	v_bfe_u32 v11, v3, 16, 1
	v_bfe_u32 v12, v2, 16, 1
	v_add3_u32 v12, v2, v12, s54
	v_add3_u32 v11, v3, v11, s54
	v_add3_u32 v2, v6, v10, s54
	v_add3_u32 v3, v7, v8, s54
	v_bfe_u32 v6, v0, 16, 1
	v_bfe_u32 v7, v1, 16, 1
	v_bfe_u32 v8, v4, 16, 1
	v_bfe_u32 v10, v5, 16, 1
	v_add3_u32 v5, v5, v10, s54
	v_add3_u32 v4, v4, v8, s54
	v_add3_u32 v1, v1, v7, s54
	v_add3_u32 v0, v0, v6, s54
	v_lshrrev_b32_e32 v0, 16, v0
	v_lshrrev_b32_e32 v1, 16, v1
	v_lshrrev_b32_e32 v4, 16, v4
	v_lshrrev_b32_e32 v5, 16, v5
	v_and_or_b32 v3, v3, s33, v5
	v_and_or_b32 v2, v2, s33, v4
	v_and_or_b32 v1, v11, s33, v1
	v_and_or_b32 v0, v12, s33, v0
	ds_write_b128 v43, v[0:3] offset:17536
	s_and_saveexec_b64 s[22:23], vcc
	s_cbranch_execz .LBB0_405
	v_mul_f32_e32 v0, 0x42040000, v21
	v_exp_f32_e32 v0, v0
	v_lshl_add_u32 v1, v20, 2, 0
	v_add_u32_e32 v1, 0x1fc00, v1
	ds_write_b32 v1, v0
.LBB0_405:
	s_or_b64 exec, exec, s[22:23]
	v_and_b32_e32 v0, 0x78, v9
	v_ashrrev_i32_e32 v24, 4, v20
	s_ashr_i32 s17, s16, 31
	s_mul_i32 s1, s16, 0x1e00
	v_lshlrev_b32_e32 v156, 1, v0
	v_lshlrev_b32_e32 v0, 1, v24
	s_mul_hi_i32 s0, s16, 0x1e00
	s_add_u32 s1, s20, s1
	v_ashrrev_i32_e32 v1, 31, v0
	v_lshlrev_b32_e32 v2, 1, v9
	s_addc_u32 s5, s21, s0
	s_lshl_b32 s0, s3, 1
	v_lshlrev_b64 v[0:1], 8, v[0:1]
	v_and_b32_e32 v2, 0xf0, v2
	s_add_u32 s20, s1, s0
	v_or_b32_e32 v0, v0, v2
	s_addc_u32 s21, s5, 0
	v_lshl_add_u64 v[0:1], s[18:19], 0, v[0:1]
	v_lshl_add_u64 v[22:23], s[20:21], 0, v[156:157]
	v_lshl_add_u64 v[0:1], v[0:1], 0, s[6:7]
	v_add_u32_e32 v21, 0x200, v20
	s_waitcnt lgkmcnt(0)
	s_barrier
	global_load_dwordx4 v[8:11], v[0:1], off nt
	global_load_dwordx4 v[12:15], v[0:1], off offset:256 nt
	v_mad_i64_i32 v[0:1], s[20:21], v24, s83, v[22:23]
	v_ashrrev_i32_e32 v26, 4, v21
	global_load_dwordx4 v[34:37], v[0:1], off offset:3072 nt
	v_lshlrev_b32_e32 v0, 1, v26
	v_ashrrev_i32_e32 v1, 31, v0
	v_lshlrev_b64 v[0:1], 8, v[0:1]
	v_or_b32_e32 v0, v0, v2
	v_lshl_add_u64 v[0:1], s[18:19], 0, v[0:1]
	v_lshl_add_u64 v[4:5], v[0:1], 0, s[6:7]
	v_mad_i64_i32 v[22:23], s[18:19], v26, s83, v[22:23]
	global_load_dwordx4 v[0:3], v[4:5], off nt
	s_nop 0
	global_load_dwordx4 v[4:7], v[4:5], off offset:256 nt
	v_lshlrev_b32_e32 v16, 4, v18
	global_load_dwordx4 v[38:41], v[22:23], off offset:3072 nt
	v_and_b32_e32 v16, 0xf0, v16
	v_add_u32_e32 v16, s43, v16
	v_mul_lo_u32 v31, v24, s29
	v_mul_lo_u32 v30, v26, s29
	v_readfirstlane_b32 s1, v20
	v_add_u32_e32 v20, v16, v31
	v_add_u32_e32 v16, v16, v30
	v_and_b32_e32 v22, 0x3ffffffe, v19
	s_add_i32 s5, 0, 0x1fc00
	v_lshl_add_u32 v22, v22, 2, s5
	v_lshl_or_b32 v23, v19, 2, 4
	v_add_u32_e32 v23, s5, v23
	v_and_b32_e32 v25, -8, v19
	v_and_b32_e32 v27, 6, v19
	v_lshlrev_b32_e32 v27, 1, v27
	s_ashr_i32 s18, s1, 3
	v_and_b32_e32 v32, 15, v18
	s_bfe_u32 s1, s1, 0x10006
	v_lshrrev_b32_e32 v17, 4, v18
	s_waitcnt vmcnt(5)
	v_lshlrev_b32_e32 v28, 16, v8
	s_waitcnt vmcnt(4)
	v_lshlrev_b32_e32 v29, 16, v12
	v_and_b32_e32 v8, 0xffff0000, v8
	v_and_b32_e32 v12, 0xffff0000, v12
	s_waitcnt vmcnt(3)
	ds_write_b128 v20, v[34:37]
	v_lshlrev_b32_e32 v20, 5, v18
	s_waitcnt vmcnt(0)
	ds_write_b128 v16, v[38:41]
	ds_read_b32 v22, v22
	ds_read_b32 v23, v23
	v_and_b32_e32 v16, 12, v18
	v_and_or_b32 v20, v20, s44, v16
	v_bitop3_b32 v33, v20, v25, 40 bitop3:0x6c
	s_waitcnt lgkmcnt(1)
	v_mul_f32_e32 v28, v22, v28
	s_waitcnt lgkmcnt(0)
	v_mul_f32_e32 v29, v23, v29
	v_bfe_u32 v34, v28, 16, 1
	v_add3_u32 v28, v28, v34, s54
	v_bfe_u32 v34, v29, 16, 1
	v_lshrrev_b32_e32 v28, 16, v28
	v_add3_u32 v29, v29, v34, s54
	v_mul_f32_e32 v8, v22, v8
	v_and_or_b32 v28, v29, s33, v28
	v_mul_f32_e32 v12, v23, v12
	v_bfe_u32 v29, v8, 16, 1
	v_mad_u32_u24 v19, v20, s29, 0
	v_lshlrev_b32_e32 v33, 1, v33
	v_add3_u32 v8, v8, v29, s54
	v_bfe_u32 v29, v12, 16, 1
	v_add3_u32 v33, v19, v33, v27
	v_lshrrev_b32_e32 v8, 16, v8
	v_add3_u32 v12, v12, v29, s54
	v_and_or_b32 v8, v12, s33, v8
	v_add_u32_e32 v12, 0xf400, v33
	ds_write2_b32 v12, v28, v8 offset1:68
	v_lshlrev_b32_e32 v8, 16, v9
	v_lshlrev_b32_e32 v28, 16, v13
	v_mul_f32_e32 v8, v22, v8
	v_mul_f32_e32 v28, v23, v28
	v_bfe_u32 v29, v8, 16, 1
	v_add3_u32 v8, v8, v29, s54
	v_bfe_u32 v29, v28, 16, 1
	v_and_b32_e32 v9, 0xffff0000, v9
	v_lshrrev_b32_e32 v8, 16, v8
	v_add3_u32 v28, v28, v29, s54
	v_and_b32_e32 v13, 0xffff0000, v13
	v_mul_f32_e32 v9, v22, v9
	v_and_or_b32 v8, v28, s33, v8
	v_mul_f32_e32 v13, v23, v13
	v_bfe_u32 v28, v9, 16, 1
	v_add3_u32 v9, v9, v28, s54
	v_bfe_u32 v28, v13, 16, 1
	v_lshrrev_b32_e32 v9, 16, v9
	v_add3_u32 v13, v13, v28, s54
	v_and_or_b32 v9, v13, s33, v9
	ds_write2_b32 v12, v8, v9 offset0:136 offset1:204
	v_lshlrev_b32_e32 v12, 16, v10
	v_lshlrev_b32_e32 v13, 16, v14
	v_mul_f32_e32 v12, v22, v12
	v_or_b32_e32 v8, 16, v20
	v_mul_f32_e32 v13, v23, v13
	v_bfe_u32 v29, v12, 16, 1
	v_bitop3_b32 v25, v8, v25, 56 bitop3:0x6c
	v_add3_u32 v12, v12, v29, s54
	v_bfe_u32 v29, v13, 16, 1
	v_mad_u32_u24 v9, v8, s29, 0
	v_lshlrev_b32_e32 v25, 1, v25
	v_lshrrev_b32_e32 v12, 16, v12
	v_add3_u32 v13, v13, v29, s54
	v_add3_u32 v28, v9, v25, v27
	v_and_or_b32 v12, v13, s33, v12
	v_and_b32_e32 v10, 0xffff0000, v10
	ds_write_b32 v28, v12 offset:62464
	v_and_b32_e32 v12, 0xffff0000, v14
	v_mul_f32_e32 v10, v22, v10
	v_mul_f32_e32 v12, v23, v12
	v_bfe_u32 v14, v10, 16, 1
	v_add3_u32 v10, v10, v14, s54
	v_bfe_u32 v14, v12, 16, 1
	v_lshrrev_b32_e32 v10, 16, v10
	v_add3_u32 v12, v12, v14, s54
	v_and_or_b32 v10, v12, s33, v10
	v_lshlrev_b32_e32 v12, 16, v11
	v_add_u32_e32 v16, 0xf400, v19
	v_lshlrev_b32_e32 v14, 16, v15
	v_mul_f32_e32 v12, v22, v12
	v_add3_u32 v13, v16, v25, v27
	v_mul_f32_e32 v14, v23, v14
	v_bfe_u32 v25, v12, 16, 1
	v_add3_u32 v12, v12, v25, s54
	v_bfe_u32 v25, v14, 16, 1
	v_lshrrev_b32_e32 v12, 16, v12
	v_add3_u32 v14, v14, v25, s54
	v_and_or_b32 v12, v14, s33, v12
	v_add_u32_e32 v14, 0x1000, v13
	ds_write2_b32 v14, v10, v12 offset0:132 offset1:200
	v_and_b32_e32 v10, 0xffff0000, v11
	v_and_b32_e32 v11, 0xffff0000, v15
	v_mul_f32_e32 v10, v22, v10
	v_mul_f32_e32 v11, v23, v11
	v_bfe_u32 v12, v10, 16, 1
	v_add3_u32 v10, v10, v12, s54
	v_bfe_u32 v12, v11, 16, 1
	v_lshrrev_b32_e32 v10, 16, v10
	v_add3_u32 v11, v11, v12, s54
	v_and_or_b32 v10, v11, s33, v10
	ds_write_b32 v13, v10 offset:5168
	v_ashrrev_i32_e32 v10, 3, v21
	v_lshlrev_b32_e32 v11, 2, v10
	v_and_b32_e32 v12, -8, v11
	v_add_u32_e32 v12, s5, v12
	v_or_b32_e32 v11, 4, v11
	ds_read_b32 v12, v12
	v_add_u32_e32 v11, s5, v11
	ds_read_b32 v11, v11
	v_and_b32_e32 v13, -8, v10
	v_lshlrev_b32_e32 v14, 16, v0
	v_bitop3_b32 v20, v20, v13, 40 bitop3:0x6c
	v_lshlrev_b32_e32 v10, 1, v10
	v_lshlrev_b32_e32 v15, 16, v4
	v_lshlrev_b32_e32 v20, 1, v20
	v_and_b32_e32 v10, 12, v10
	s_waitcnt lgkmcnt(1)
	v_mul_f32_e32 v14, v12, v14
	v_add3_u32 v19, v19, v20, v10
	s_waitcnt lgkmcnt(0)
	v_mul_f32_e32 v15, v11, v15
	v_bfe_u32 v20, v14, 16, 1
	v_add3_u32 v14, v14, v20, s54
	v_bfe_u32 v20, v15, 16, 1
	v_and_b32_e32 v0, 0xffff0000, v0
	v_lshrrev_b32_e32 v14, 16, v14
	v_add3_u32 v15, v15, v20, s54
	v_and_b32_e32 v4, 0xffff0000, v4
	v_mul_f32_e32 v0, v12, v0
	v_and_or_b32 v14, v15, s33, v14
	v_mul_f32_e32 v4, v11, v4
	v_bfe_u32 v15, v0, 16, 1
	v_add3_u32 v0, v0, v15, s54
	v_bfe_u32 v15, v4, 16, 1
	v_lshrrev_b32_e32 v0, 16, v0
	v_add3_u32 v4, v4, v15, s54
	v_and_or_b32 v0, v4, s33, v0
	v_add_u32_e32 v4, 0xf400, v19
	ds_write2_b32 v4, v14, v0 offset1:68
	v_lshlrev_b32_e32 v0, 16, v1
	v_lshlrev_b32_e32 v14, 16, v5
	v_mul_f32_e32 v0, v12, v0
	v_mul_f32_e32 v14, v11, v14
	v_bfe_u32 v15, v0, 16, 1
	v_add3_u32 v0, v0, v15, s54
	v_bfe_u32 v15, v14, 16, 1
	v_and_b32_e32 v1, 0xffff0000, v1
	v_lshrrev_b32_e32 v0, 16, v0
	v_add3_u32 v14, v14, v15, s54
	v_and_b32_e32 v5, 0xffff0000, v5
	v_mul_f32_e32 v1, v12, v1
	v_and_or_b32 v0, v14, s33, v0
	v_mul_f32_e32 v5, v11, v5
	v_bfe_u32 v14, v1, 16, 1
	v_add3_u32 v1, v1, v14, s54
	v_bfe_u32 v14, v5, 16, 1
	v_lshrrev_b32_e32 v1, 16, v1
	v_add3_u32 v5, v5, v14, s54
	v_and_or_b32 v1, v5, s33, v1
	ds_write2_b32 v4, v0, v1 offset0:136 offset1:204
	v_lshlrev_b32_e32 v0, 16, v2
	v_lshlrev_b32_e32 v1, 16, v6
	v_mul_f32_e32 v0, v12, v0
	v_bitop3_b32 v4, v8, v13, 56 bitop3:0x6c
	v_mul_f32_e32 v1, v11, v1
	v_bfe_u32 v8, v0, 16, 1
	v_add3_u32 v0, v0, v8, s54
	v_bfe_u32 v8, v1, 16, 1
	v_lshlrev_b32_e32 v4, 1, v4
	v_lshrrev_b32_e32 v0, 16, v0
	v_add3_u32 v1, v1, v8, s54
	v_add3_u32 v5, v9, v4, v10
	v_and_or_b32 v0, v1, s33, v0
	ds_write_b32 v5, v0 offset:62464
	v_and_b32_e32 v0, 0xffff0000, v2
	v_and_b32_e32 v1, 0xffff0000, v6
	v_mul_f32_e32 v0, v12, v0
	v_add3_u32 v2, v16, v4, v10
	v_mul_f32_e32 v1, v11, v1
	v_bfe_u32 v4, v0, 16, 1
	v_add3_u32 v0, v0, v4, s54
	v_bfe_u32 v4, v1, 16, 1
	v_lshrrev_b32_e32 v0, 16, v0
	v_add3_u32 v1, v1, v4, s54
	v_and_or_b32 v0, v1, s33, v0
	v_lshlrev_b32_e32 v1, 16, v3
	v_lshlrev_b32_e32 v4, 16, v7
	v_mul_f32_e32 v1, v12, v1
	v_mul_f32_e32 v4, v11, v4
	v_bfe_u32 v5, v1, 16, 1
	v_add3_u32 v1, v1, v5, s54
	v_bfe_u32 v5, v4, 16, 1
	v_lshrrev_b32_e32 v1, 16, v1
	v_add3_u32 v4, v4, v5, s54
	v_and_or_b32 v1, v4, s33, v1
	v_add_u32_e32 v4, 0x1000, v2
	ds_write2_b32 v4, v0, v1 offset0:132 offset1:200
	v_and_b32_e32 v0, 0xffff0000, v3
	v_and_b32_e32 v1, 0xffff0000, v7
	v_mul_f32_e32 v0, v12, v0
	v_mul_f32_e32 v1, v11, v1
	v_bfe_u32 v3, v0, 16, 1
	v_add3_u32 v0, v0, v3, s54
	v_bfe_u32 v3, v1, 16, 1
	v_lshrrev_b32_e32 v0, 16, v0
	v_add3_u32 v1, v1, v3, s54
	v_and_or_b32 v0, v1, s33, v0
	v_bfe_u32 v22, v18, 4, 2
	v_bfi_b32 v23, -16, s18, v18
	ds_write_b32 v2, v0 offset:5168
	v_mul_lo_u32 v0, v23, s29
	v_lshlrev_b32_e32 v25, 4, v22
	v_lshl_or_b32 v16, s1, 5, v32
	v_add3_u32 v27, 0, v0, v25
	v_mul_u32_u24_e32 v0, 0x110, v16
	v_add3_u32 v19, 0, v0, v25
	ds_read_b128 v[0:3], v27
	ds_read_b128 v[4:7], v19 offset:17408
	ds_read_b128 v[8:11], v19 offset:21760
	s_waitcnt lgkmcnt(1)
	v_mfma_f32_16x16x32_bf16 v[4:7], v[0:3], v[4:7], 0
	s_and_b32 s5, s18, -16
	v_lshl_or_b32 v33, v22, 2, s5
	v_cmp_le_i32_e32 vcc, v16, v33
	s_waitcnt lgkmcnt(0)
	v_mfma_f32_16x16x32_bf16 v[0:3], v[0:3], v[8:11], 0
	ds_read_b128 v[8:11], v27 offset:64
	ds_read_b128 v[12:15], v19 offset:17472
	s_lshl_b32 s1, s1, 6
	v_bfe_u32 v29, v18, 3, 1
	s_waitcnt lgkmcnt(0)
	v_mfma_f32_16x16x32_bf16 v[4:7], v[8:11], v[12:15], v[4:7]
	ds_read_b128 v[12:15], v19 offset:21824
	v_or_b32_e32 v18, 48, v32
	v_lshrrev_b32_e32 v46, 3, v18
	s_waitcnt lgkmcnt(0)
	v_mfma_f32_16x16x32_bf16 v[0:3], v[8:11], v[12:15], v[0:3]
	ds_read_b128 v[8:11], v27 offset:128
	ds_read_b128 v[12:15], v19 offset:17536
	v_bitop3_b32 v34, v22, v29, 4 bitop3:0x36
	v_lshlrev_b32_e32 v47, 4, v34
	s_waitcnt lgkmcnt(0)
	v_mfma_f32_16x16x32_bf16 v[4:7], v[8:11], v[12:15], v[4:7]
	ds_read_b128 v[12:15], v19 offset:21888
	s_waitcnt lgkmcnt(0)
	v_mfma_f32_16x16x32_bf16 v[0:3], v[8:11], v[12:15], v[0:3]
	ds_read_b128 v[8:11], v27 offset:192
	ds_read_b128 v[12:15], v19 offset:17600
	s_waitcnt lgkmcnt(0)
	v_mfma_f32_16x16x32_bf16 v[4:7], v[8:11], v[12:15], v[4:7]
	ds_read_b128 v[12:15], v19 offset:21952
	s_waitcnt lgkmcnt(0)
	v_mfma_f32_16x16x32_bf16 v[0:3], v[8:11], v[12:15], v[0:3]
	s_nop 4
	v_cndmask_b32_e32 v4, 0, v4, vcc
	v_or_b32_e32 v8, 16, v16
	v_bfe_u32 v9, v4, 16, 1
	v_add3_u32 v4, v4, v9, s54
	v_mul_lo_u32 v9, v33, s85
	v_lshlrev_b32_e32 v10, 1, v16
	v_cmp_le_i32_e32 vcc, v8, v33
	v_add3_u32 v9, 0, v9, v10
	ds_write_b16_d16_hi v9, v4 offset:34816
	v_cndmask_b32_e32 v0, 0, v0, vcc
	v_bfe_u32 v4, v0, 16, 1
	v_add3_u32 v0, v0, v4, s54
	ds_write_b16_d16_hi v9, v0 offset:34848
	v_or_b32_e32 v0, 1, v33
	v_cmp_le_i32_e32 vcc, v16, v0
	v_or_b32_e32 v12, 32, v32
	v_lshrrev_b32_e32 v43, 3, v12
	v_cndmask_b32_e32 v4, 0, v5, vcc
	v_cmp_le_i32_e32 vcc, v8, v0
	v_bfe_u32 v5, v4, 16, 1
	v_add3_u32 v4, v4, v5, s54
	v_cndmask_b32_e32 v0, 0, v1, vcc
	v_bfe_u32 v1, v0, 16, 1
	v_add3_u32 v0, v0, v1, s54
	ds_write_b16_d16_hi v9, v0 offset:34992
	v_or_b32_e32 v0, 2, v33
	v_cmp_le_i32_e32 vcc, v16, v0
	ds_write_b16_d16_hi v9, v4 offset:34960
	v_bitop3_b32 v12, v43, v17, 3 bitop3:0x78
	v_cndmask_b32_e32 v1, 0, v6, vcc
	v_bfe_u32 v4, v1, 16, 1
	v_cmp_le_i32_e32 vcc, v8, v0
	v_add3_u32 v1, v1, v4, s54
	ds_write_b16_d16_hi v9, v1 offset:35104
	v_cndmask_b32_e32 v0, 0, v2, vcc
	v_bfe_u32 v1, v0, 16, 1
	v_add3_u32 v0, v0, v1, s54
	ds_write_b16_d16_hi v9, v0 offset:35136
	v_or_b32_e32 v0, 3, v33
	v_cmp_le_i32_e32 vcc, v16, v0
	v_or_b32_e32 v16, s1, v32
	v_mad_u32_u24 v28, v16, s29, 0
	v_cndmask_b32_e32 v1, 0, v7, vcc
	v_bfe_u32 v2, v1, 16, 1
	v_cmp_le_i32_e32 vcc, v8, v0
	v_add3_u32 v1, v1, v2, s54
	ds_write_b16_d16_hi v9, v1 offset:35248
	v_cndmask_b32_e32 v0, 0, v3, vcc
	v_bfe_u32 v1, v0, 16, 1
	v_add3_u32 v0, v0, v1, s54
	v_or_b32_e32 v8, 16, v32
	ds_write_b16_d16_hi v9, v0 offset:35280
	s_waitcnt lgkmcnt(0)
	s_barrier
	ds_read_b128 v[0:3], v27
	v_lshrrev_b32_e32 v40, 3, v8
	v_bitop3_b32 v4, v29, v17, 3 bitop3:0x78
	v_bitop3_b32 v8, v40, v17, 3 bitop3:0x78
	v_bitop3_b32 v17, v46, v17, 3 bitop3:0x78
	v_lshlrev_b32_e32 v38, 4, v4
	v_add_u32_e32 v39, 0x1100, v28
	v_lshlrev_b32_e32 v41, 4, v8
	v_add_u32_e32 v42, 0x2200, v28
	v_lshlrev_b32_e32 v44, 4, v12
	v_add_u32_e32 v45, 0x3300, v28
	v_lshlrev_b32_e32 v17, 4, v17
	v_add_u32_e32 v4, v28, v38
	v_add_u32_e32 v8, v39, v41
	v_add_u32_e32 v12, v42, v44
	v_add_u32_e32 v18, v45, v17
	ds_read_b128 v[4:7], v4 offset:62464
	ds_read_b128 v[8:11], v8 offset:62464
	ds_read_b128 v[12:15], v12 offset:62464
	ds_read_b128 v[18:21], v18 offset:62464
	v_add_u32_e32 v34, v28, v47
	ds_read_b128 v[34:37], v34 offset:62464
	s_waitcnt lgkmcnt(4)
	v_mfma_f32_16x16x32_bf16 v[4:7], v[0:3], v[4:7], 0
	v_cmp_eq_u32_e32 vcc, 0, v32
	s_waitcnt lgkmcnt(3)
	v_mfma_f32_16x16x32_bf16 v[8:11], v[0:3], v[8:11], 0
	s_waitcnt lgkmcnt(2)
	v_mfma_f32_16x16x32_bf16 v[12:15], v[0:3], v[12:15], 0
	s_waitcnt lgkmcnt(1)
	v_mfma_f32_16x16x32_bf16 v[0:3], v[0:3], v[18:21], 0
	ds_read_b128 v[18:21], v27 offset:64
	s_waitcnt lgkmcnt(0)
	v_mfma_f32_16x16x32_bf16 v[4:7], v[18:21], v[34:37], v[4:7]
	v_bitop3_b32 v34, v40, v22, 4 bitop3:0x1e
	v_lshlrev_b32_e32 v48, 4, v34
	v_add_u32_e32 v34, v39, v48
	ds_read_b128 v[34:37], v34 offset:62464
	s_waitcnt lgkmcnt(0)
	v_mfma_f32_16x16x32_bf16 v[8:11], v[18:21], v[34:37], v[8:11]
	v_bitop3_b32 v34, v43, v22, 4 bitop3:0x1e
	v_lshlrev_b32_e32 v49, 4, v34
	v_add_u32_e32 v34, v42, v49
	ds_read_b128 v[34:37], v34 offset:62464
	s_waitcnt lgkmcnt(0)
	v_mfma_f32_16x16x32_bf16 v[12:15], v[18:21], v[34:37], v[12:15]
	v_bitop3_b32 v34, v46, v22, 4 bitop3:0x1e
	v_lshlrev_b32_e32 v50, 4, v34
	v_add_u32_e32 v34, v45, v50
	ds_read_b128 v[34:37], v34 offset:62464
	s_waitcnt lgkmcnt(0)
	v_mfma_f32_16x16x32_bf16 v[0:3], v[18:21], v[34:37], v[0:3]
	ds_read_b128 v[18:21], v27 offset:128
	v_bitop3_b32 v34, v22, v29, 8 bitop3:0x36
	v_lshl_add_u32 v34, v34, 4, v28
	ds_read_b128 v[34:37], v34 offset:62464
	s_waitcnt lgkmcnt(0)
	v_mfma_f32_16x16x32_bf16 v[4:7], v[18:21], v[34:37], v[4:7]
	v_bitop3_b32 v34, v40, v22, 8 bitop3:0x1e
	v_lshl_add_u32 v34, v34, 4, v39
	ds_read_b128 v[34:37], v34 offset:62464
	s_waitcnt lgkmcnt(0)
	v_mfma_f32_16x16x32_bf16 v[8:11], v[18:21], v[34:37], v[8:11]
	v_bitop3_b32 v34, v43, v22, 8 bitop3:0x1e
	v_lshl_add_u32 v34, v34, 4, v42
	ds_read_b128 v[34:37], v34 offset:62464
	s_waitcnt lgkmcnt(0)
	v_mfma_f32_16x16x32_bf16 v[12:15], v[18:21], v[34:37], v[12:15]
	v_bitop3_b32 v34, v46, v22, 8 bitop3:0x1e
	v_lshl_add_u32 v34, v34, 4, v45
	ds_read_b128 v[34:37], v34 offset:62464
	s_waitcnt lgkmcnt(0)
	v_mfma_f32_16x16x32_bf16 v[0:3], v[18:21], v[34:37], v[0:3]
	ds_read_b128 v[18:21], v27 offset:192
	v_bitop3_b32 v27, v22, v29, 12 bitop3:0x36
	v_lshl_add_u32 v27, v27, 4, v28
	ds_read_b128 v[34:37], v27 offset:62464
	v_bitop3_b32 v27, v40, v22, 12 bitop3:0x1e
	v_lshl_add_u32 v27, v27, 4, v39
	s_waitcnt lgkmcnt(0)
	v_mfma_f32_16x16x32_bf16 v[4:7], v[18:21], v[34:37], v[4:7]
	ds_read_b128 v[34:37], v27 offset:62464
	v_bitop3_b32 v27, v43, v22, 12 bitop3:0x1e
	v_lshl_add_u32 v27, v27, 4, v42
	s_waitcnt lgkmcnt(0)
	v_mfma_f32_16x16x32_bf16 v[8:11], v[18:21], v[34:37], v[8:11]
	ds_read_b128 v[34:37], v27 offset:62464
	v_bitop3_b32 v22, v46, v22, 12 bitop3:0x1e
	v_lshl_add_u32 v22, v22, 4, v45
	s_waitcnt lgkmcnt(0)
	v_mfma_f32_16x16x32_bf16 v[12:15], v[18:21], v[34:37], v[12:15]
	ds_read_b128 v[34:37], v22 offset:62464
	s_waitcnt lgkmcnt(0)
	v_mfma_f32_16x16x32_bf16 v[0:3], v[18:21], v[34:37], v[0:3]
	v_mul_lo_u32 v18, v23, s85
	v_add3_u32 v22, 0, v18, v25
	ds_read_b128 v[18:21], v22 offset:34816
	v_mul_u32_u24_e32 v23, 0x90, v16
	v_add3_u32 v27, 0, v38, v23
	ds_read_b128 v[34:37], v27 offset:44032
	v_mad_u32_u24 v27, v16, s85, v198
	v_add3_u32 v28, 0, v41, v27
	s_waitcnt lgkmcnt(0)
	v_mfma_f32_16x16x32_bf16 v[4:7], v[18:21], v[34:37], v[4:7]
	ds_read_b128 v[34:37], v28 offset:44032
	v_mad_u32_u24 v28, v16, s85, v199
	v_add3_u32 v29, 0, v44, v28
	s_waitcnt lgkmcnt(0)
	v_mfma_f32_16x16x32_bf16 v[8:11], v[18:21], v[34:37], v[8:11]
	ds_read_b128 v[34:37], v29 offset:44032
	v_mad_u32_u24 v29, v16, s85, v200
	s_waitcnt lgkmcnt(0)
	v_mfma_f32_16x16x32_bf16 v[34:37], v[18:21], v[34:37], v[12:15]
	s_nop 2
	v_add3_u32 v12, 0, v17, v29
	ds_read_b128 v[12:15], v12 offset:44032
	v_add3_u32 v17, 0, v50, v29
	s_waitcnt lgkmcnt(0)
	v_mfma_f32_16x16x32_bf16 v[0:3], v[18:21], v[12:15], v[0:3]
	ds_read_b128 v[18:21], v22 offset:34880
	v_add3_u32 v12, 0, v47, v23
	ds_read_b128 v[12:15], v12 offset:44032
	s_waitcnt lgkmcnt(0)
	v_mfma_f32_16x16x32_bf16 v[12:15], v[18:21], v[12:15], v[4:7]
	s_nop 2
	v_add3_u32 v4, 0, v48, v27
	ds_read_b128 v[4:7], v4 offset:44032
	s_waitcnt lgkmcnt(0)
	v_mfma_f32_16x16x32_bf16 v[8:11], v[18:21], v[4:7], v[8:11]
	v_add3_u32 v4, 0, v49, v28
	ds_read_b128 v[4:7], v4 offset:44032
	s_waitcnt lgkmcnt(0)
	v_mfma_f32_16x16x32_bf16 v[4:7], v[18:21], v[4:7], v[34:37]
	s_nop 2
	ds_read_b128 v[34:37], v17 offset:44032
	s_waitcnt lgkmcnt(0)
	v_mfma_f32_16x16x32_bf16 v[0:3], v[18:21], v[34:37], v[0:3]
	v_mul_f32_e64 v18, v10, v10
	v_mul_f32_e64 v19, v11, v11
	v_pk_mul_f32 v[20:21], v[8:9], v[8:9]
	v_pk_fma_f32 v[18:19], v[14:15], v[14:15], v[18:19]
	s_nop 3
	v_pk_mul_f32 v[22:23], v[2:3], v[2:3]
	v_pk_mul_f32 v[28:29], v[0:1], v[0:1]
	v_pk_fma_f32 v[20:21], v[12:13], v[12:13], v[20:21]
	v_pk_fma_f32 v[22:23], v[6:7], v[6:7], v[22:23]
	v_pk_fma_f32 v[28:29], v[4:5], v[4:5], v[28:29]
	v_pk_add_f32 v[22:23], v[18:19], v[22:23]
	v_pk_add_f32 v[18:19], v[20:21], v[28:29]
	s_nop 0
	v_mov_b32_dpp v28, v22 quad_perm:[1,0,3,2] row_mask:0xf bank_mask:0xf bound_ctrl:1
	v_mov_b32_dpp v20, v18 quad_perm:[1,0,3,2] row_mask:0xf bank_mask:0xf bound_ctrl:1
	v_mov_b32_dpp v21, v19 quad_perm:[1,0,3,2] row_mask:0xf bank_mask:0xf bound_ctrl:1
	v_mov_b32_dpp v29, v23 quad_perm:[1,0,3,2] row_mask:0xf bank_mask:0xf bound_ctrl:1
	v_pk_add_f32 v[18:19], v[18:19], v[20:21]
	v_pk_add_f32 v[22:23], v[22:23], v[28:29]
	s_nop 0
	v_mov_b32_dpp v20, v18 quad_perm:[2,3,0,1] row_mask:0xf bank_mask:0xf bound_ctrl:1
	v_mov_b32_dpp v21, v19 quad_perm:[2,3,0,1] row_mask:0xf bank_mask:0xf bound_ctrl:1
	v_mov_b32_dpp v28, v22 quad_perm:[2,3,0,1] row_mask:0xf bank_mask:0xf bound_ctrl:1
	v_mov_b32_dpp v29, v23 quad_perm:[2,3,0,1] row_mask:0xf bank_mask:0xf bound_ctrl:1
	v_pk_add_f32 v[18:19], v[18:19], v[20:21]
	v_pk_add_f32 v[22:23], v[22:23], v[28:29]
	s_nop 0
	v_mov_b32_dpp v20, v18 row_half_mirror row_mask:0xf bank_mask:0xf bound_ctrl:1
	v_mov_b32_dpp v21, v19 row_half_mirror row_mask:0xf bank_mask:0xf bound_ctrl:1
	v_mov_b32_dpp v28, v22 row_half_mirror row_mask:0xf bank_mask:0xf bound_ctrl:1
	v_mov_b32_dpp v29, v23 row_half_mirror row_mask:0xf bank_mask:0xf bound_ctrl:1
	v_pk_add_f32 v[18:19], v[18:19], v[20:21]
	v_pk_add_f32 v[22:23], v[22:23], v[28:29]
	s_nop 0
	v_mov_b32_dpp v20, v18 row_mirror row_mask:0xf bank_mask:0xf bound_ctrl:1
	v_mov_b32_dpp v21, v19 row_mirror row_mask:0xf bank_mask:0xf bound_ctrl:1
	v_mov_b32_dpp v28, v22 row_mirror row_mask:0xf bank_mask:0xf bound_ctrl:1
	v_mov_b32_dpp v29, v23 row_mirror row_mask:0xf bank_mask:0xf bound_ctrl:1
	s_and_saveexec_b64 s[18:19], vcc
	s_cbranch_execz .LBB0_402
	s_lshl_b32 s1, s1, 2
	s_add_i32 s1, s1, 0
	s_lshl_b32 s5, s5, 2
	s_add_i32 s1, s1, s5
	v_add_u32_e32 v17, s1, v25
	v_add_u32_e32 v17, 0x1fe00, v17
	v_pk_add_f32 v[18:19], v[18:19], v[20:21]
	v_pk_add_f32 v[20:21], v[22:23], v[28:29]
	ds_write_b128 v17, v[18:21]
	s_branch .LBB0_402
